# LRU prompt loop: batch S4/S5a LDS reads (issue 14-16 reads up front, counted lgkmcnt) on top of batched weight transposes
# speedup vs baseline: 1.0018x; 1.0018x over previous
.LBB0_325:
	s_andn2_b64 vcc, exec, s[0:1]
	s_cbranch_vccnz .LBB0_379
	v_readlane_b32 s0, v249, 0
	s_sub_i32 s0, s0, 20
	s_cmpk_gt_u32 s0, 0xeb
	s_cbranch_scc1 .LBB0_379
	v_readlane_b32 s0, v249, 0
	s_lshl_b32 s0, s0, 3
	s_addk_i32 s0, 0xff60
	v_add_u32_e32 v0, s0, v49
	v_add_u32_e32 v10, 0x500, v0
	s_movk_i32 s0, 0x700
	v_cmp_gt_u32_e32 vcc, s0, v10
	s_and_saveexec_b64 s[2:3], vcc
	s_cbranch_execz .LBB0_363
	v_readfirstlane_b32 s32, v10
	v_and_b32_e32 v4, 63, v188
	v_and_b32_e32 v5, 31, v188
	v_lshlrev_b32_e32 v5, 2, v5
	v_lshrrev_b32_e32 v6, 5, v4
	v_and_b32_e32 v7, 7, v188
	v_lshrrev_b32_e32 v8, 3, v4
	v_lshrrev_b32_e32 v9, 6, v188
	v_lshlrev_b32_e32 v9, 14, v9
	v_mul_u32_u24_e32 v10, 0x84, v6
	v_add3_u32 v10, v10, v5, v9
	v_mul_u32_u24_e32 v11, 0x420, v7
	v_lshl_add_u32 v11, v8, 2, v11
	v_add_u32_e32 v11, v11, v9
	v_lshlrev_b32_e32 v12, 5, v7
	v_lshlrev_b32_e32 v13, 4, v7
.Lxp_item:
	s_sub_u32 s33, s32, 1280
	s_lshr_b32 s34, s33, 5
	s_and_b32 s35, s33, 31
	s_lshl_b32 s34, s34, 6
	s_lshl_b32 s35, s35, 5
	v_readlane_b32 s50, v249, 27
	v_readlane_b32 s51, v249, 28
	s_movk_i32 s45, 0x1000
	s_movk_i32 s48, 0x800
	s_add_u32 s60, s30, 0x900000
	s_addc_u32 s61, s31, 0
	s_mov_b32 s52, s35
	s_mov_b32 s49, 1
	s_cmp_lt_u32 s34, 512
	s_cbranch_scc1 .Lxp_g0_1
	v_readlane_b32 s54, v249, 25
	v_readlane_b32 s55, v249, 26
	s_sub_u32 s39, s34, 512
	s_branch .Lxp_gd_1
.Lxp_g0_1:
	v_readlane_b32 s54, v249, 23
	v_readlane_b32 s55, v249, 24
	s_mov_b32 s39, s34
.Lxp_gd_1:
	s_lshl_b32 s39, s39, 2
	s_add_u32 s40, s54, s39
	s_addc_u32 s41, s55, 0
.Lxp_common:
	s_mul_i32 s46, s34, s45
	s_lshl_b32 s47, s35, 2
	s_add_u32 s46, s46, s47
	s_add_u32 s36, s50, s46
	s_addc_u32 s37, s51, 0
	s_lshl_b32 s38, s45, 1
	s_mul_i32 s46, s52, s48
	s_lshl_b32 s47, s34, 1
	s_add_u32 s46, s46, s47
	s_add_u32 s42, s60, s46
	s_addc_u32 s43, s61, 0
	s_lshl_b32 s44, s48, 3
	v_mul_lo_u32 v14, v6, s45
	v_add_u32_e32 v14, v14, v5
	v_mul_lo_u32 v15, v8, s48
	v_add_u32_e32 v15, v15, v13
	s_cmp_eq_u32 s49, 0
	s_cbranch_scc1 .Lxp_nog_ld
	global_load_dwordx4 v[48:51], v12, s[40:41]
	global_load_dwordx4 v[52:55], v12, s[40:41] offset:16
	s_branch .Lxp_ld
.Lxp_nog_ld:
	v_mov_b32_e32 v48, 1.0
	v_mov_b32_e32 v49, 1.0
	v_mov_b32_e32 v50, 1.0
	v_mov_b32_e32 v51, 1.0
	v_mov_b32_e32 v52, 1.0
	v_mov_b32_e32 v53, 1.0
	v_mov_b32_e32 v54, 1.0
	v_mov_b32_e32 v55, 1.0
.Lxp_ld:
	global_load_dword v16, v14, s[36:37]
	s_add_u32 s36, s36, s38
	s_addc_u32 s37, s37, 0
	global_load_dword v17, v14, s[36:37]
	s_add_u32 s36, s36, s38
	s_addc_u32 s37, s37, 0
	global_load_dword v18, v14, s[36:37]
	s_add_u32 s36, s36, s38
	s_addc_u32 s37, s37, 0
	global_load_dword v19, v14, s[36:37]
	s_add_u32 s36, s36, s38
	s_addc_u32 s37, s37, 0
	global_load_dword v20, v14, s[36:37]
	s_add_u32 s36, s36, s38
	s_addc_u32 s37, s37, 0
	global_load_dword v21, v14, s[36:37]
	s_add_u32 s36, s36, s38
	s_addc_u32 s37, s37, 0
	global_load_dword v22, v14, s[36:37]
	s_add_u32 s36, s36, s38
	s_addc_u32 s37, s37, 0
	global_load_dword v23, v14, s[36:37]
	s_add_u32 s36, s36, s38
	s_addc_u32 s37, s37, 0
	global_load_dword v24, v14, s[36:37]
	s_add_u32 s36, s36, s38
	s_addc_u32 s37, s37, 0
	global_load_dword v25, v14, s[36:37]
	s_add_u32 s36, s36, s38
	s_addc_u32 s37, s37, 0
	global_load_dword v26, v14, s[36:37]
	s_add_u32 s36, s36, s38
	s_addc_u32 s37, s37, 0
	global_load_dword v27, v14, s[36:37]
	s_add_u32 s36, s36, s38
	s_addc_u32 s37, s37, 0
	global_load_dword v28, v14, s[36:37]
	s_add_u32 s36, s36, s38
	s_addc_u32 s37, s37, 0
	global_load_dword v29, v14, s[36:37]
	s_add_u32 s36, s36, s38
	s_addc_u32 s37, s37, 0
	global_load_dword v30, v14, s[36:37]
	s_add_u32 s36, s36, s38
	s_addc_u32 s37, s37, 0
	global_load_dword v31, v14, s[36:37]
	s_add_u32 s36, s36, s38
	s_addc_u32 s37, s37, 0
	global_load_dword v32, v14, s[36:37]
	s_add_u32 s36, s36, s38
	s_addc_u32 s37, s37, 0
	global_load_dword v33, v14, s[36:37]
	s_add_u32 s36, s36, s38
	s_addc_u32 s37, s37, 0
	global_load_dword v34, v14, s[36:37]
	s_add_u32 s36, s36, s38
	s_addc_u32 s37, s37, 0
	global_load_dword v35, v14, s[36:37]
	s_add_u32 s36, s36, s38
	s_addc_u32 s37, s37, 0
	global_load_dword v36, v14, s[36:37]
	s_add_u32 s36, s36, s38
	s_addc_u32 s37, s37, 0
	global_load_dword v37, v14, s[36:37]
	s_add_u32 s36, s36, s38
	s_addc_u32 s37, s37, 0
	global_load_dword v38, v14, s[36:37]
	s_add_u32 s36, s36, s38
	s_addc_u32 s37, s37, 0
	global_load_dword v39, v14, s[36:37]
	s_add_u32 s36, s36, s38
	s_addc_u32 s37, s37, 0
	global_load_dword v40, v14, s[36:37]
	s_add_u32 s36, s36, s38
	s_addc_u32 s37, s37, 0
	global_load_dword v41, v14, s[36:37]
	s_add_u32 s36, s36, s38
	s_addc_u32 s37, s37, 0
	global_load_dword v42, v14, s[36:37]
	s_add_u32 s36, s36, s38
	s_addc_u32 s37, s37, 0
	global_load_dword v43, v14, s[36:37]
	s_add_u32 s36, s36, s38
	s_addc_u32 s37, s37, 0
	global_load_dword v44, v14, s[36:37]
	s_add_u32 s36, s36, s38
	s_addc_u32 s37, s37, 0
	global_load_dword v45, v14, s[36:37]
	s_add_u32 s36, s36, s38
	s_addc_u32 s37, s37, 0
	global_load_dword v46, v14, s[36:37]
	s_add_u32 s36, s36, s38
	s_addc_u32 s37, s37, 0
	global_load_dword v47, v14, s[36:37]
	s_waitcnt vmcnt(31)
	ds_write_b32 v10, v16
	s_waitcnt vmcnt(30)
	ds_write_b32 v10, v17 offset:264
	s_waitcnt vmcnt(29)
	ds_write_b32 v10, v18 offset:528
	s_waitcnt vmcnt(28)
	ds_write_b32 v10, v19 offset:792
	s_waitcnt vmcnt(27)
	ds_write_b32 v10, v20 offset:1056
	s_waitcnt vmcnt(26)
	ds_write_b32 v10, v21 offset:1320
	s_waitcnt vmcnt(25)
	ds_write_b32 v10, v22 offset:1584
	s_waitcnt vmcnt(24)
	ds_write_b32 v10, v23 offset:1848
	s_waitcnt vmcnt(23)
	ds_write_b32 v10, v24 offset:2112
	s_waitcnt vmcnt(22)
	ds_write_b32 v10, v25 offset:2376
	s_waitcnt vmcnt(21)
	ds_write_b32 v10, v26 offset:2640
	s_waitcnt vmcnt(20)
	ds_write_b32 v10, v27 offset:2904
	s_waitcnt vmcnt(19)
	ds_write_b32 v10, v28 offset:3168
	s_waitcnt vmcnt(18)
	ds_write_b32 v10, v29 offset:3432
	s_waitcnt vmcnt(17)
	ds_write_b32 v10, v30 offset:3696
	s_waitcnt vmcnt(16)
	ds_write_b32 v10, v31 offset:3960
	s_waitcnt vmcnt(15)
	ds_write_b32 v10, v32 offset:4224
	s_waitcnt vmcnt(14)
	ds_write_b32 v10, v33 offset:4488
	s_waitcnt vmcnt(13)
	ds_write_b32 v10, v34 offset:4752
	s_waitcnt vmcnt(12)
	ds_write_b32 v10, v35 offset:5016
	s_waitcnt vmcnt(11)
	ds_write_b32 v10, v36 offset:5280
	s_waitcnt vmcnt(10)
	ds_write_b32 v10, v37 offset:5544
	s_waitcnt vmcnt(9)
	ds_write_b32 v10, v38 offset:5808
	s_waitcnt vmcnt(8)
	ds_write_b32 v10, v39 offset:6072
	s_waitcnt vmcnt(7)
	ds_write_b32 v10, v40 offset:6336
	s_waitcnt vmcnt(6)
	ds_write_b32 v10, v41 offset:6600
	s_waitcnt vmcnt(5)
	ds_write_b32 v10, v42 offset:6864
	s_waitcnt vmcnt(4)
	ds_write_b32 v10, v43 offset:7128
	s_waitcnt vmcnt(3)
	ds_write_b32 v10, v44 offset:7392
	s_waitcnt vmcnt(2)
	ds_write_b32 v10, v45 offset:7656
	s_waitcnt vmcnt(1)
	ds_write_b32 v10, v46 offset:7920
	s_waitcnt vmcnt(0)
	ds_write_b32 v10, v47 offset:8184
	s_waitcnt lgkmcnt(0)
	ds_read2_b32 v[56:57], v11 offset0:0 offset1:33
	ds_read2_b32 v[58:59], v11 offset0:66 offset1:99
	ds_read2_b32 v[60:61], v11 offset0:132 offset1:165
	ds_read2_b32 v[62:63], v11 offset0:198 offset1:231
	ds_read2_b32 v[64:65], v11 offset0:8 offset1:41
	ds_read2_b32 v[66:67], v11 offset0:74 offset1:107
	ds_read2_b32 v[68:69], v11 offset0:140 offset1:173
	ds_read2_b32 v[70:71], v11 offset0:206 offset1:239
	s_waitcnt lgkmcnt(4)
	v_pk_mul_f32 v[56:57], v[56:57], v[48:49]
	v_pk_mul_f32 v[58:59], v[58:59], v[50:51]
	v_pk_mul_f32 v[60:61], v[60:61], v[52:53]
	v_pk_mul_f32 v[62:63], v[62:63], v[54:55]
	v_cvt_pk_bf16_f32 v88, v56, v57
	v_cvt_pk_bf16_f32 v89, v58, v59
	v_cvt_pk_bf16_f32 v90, v60, v61
	v_cvt_pk_bf16_f32 v91, v62, v63
	global_store_dwordx4 v15, v[88:91], s[42:43]
	s_add_u32 s42, s42, s44
	s_addc_u32 s43, s43, 0
	ds_read2_b32 v[72:73], v11 offset0:16 offset1:49
	ds_read2_b32 v[74:75], v11 offset0:82 offset1:115
	ds_read2_b32 v[76:77], v11 offset0:148 offset1:181
	ds_read2_b32 v[78:79], v11 offset0:214 offset1:247
	s_waitcnt lgkmcnt(4)
	v_pk_mul_f32 v[64:65], v[64:65], v[48:49]
	v_pk_mul_f32 v[66:67], v[66:67], v[50:51]
	v_pk_mul_f32 v[68:69], v[68:69], v[52:53]
	v_pk_mul_f32 v[70:71], v[70:71], v[54:55]
	v_cvt_pk_bf16_f32 v92, v64, v65
	v_cvt_pk_bf16_f32 v93, v66, v67
	v_cvt_pk_bf16_f32 v94, v68, v69
	v_cvt_pk_bf16_f32 v95, v70, v71
	global_store_dwordx4 v15, v[92:95], s[42:43]
	s_add_u32 s42, s42, s44
	s_addc_u32 s43, s43, 0
	ds_read2_b32 v[80:81], v11 offset0:24 offset1:57
	ds_read2_b32 v[82:83], v11 offset0:90 offset1:123
	ds_read2_b32 v[84:85], v11 offset0:156 offset1:189
	ds_read2_b32 v[86:87], v11 offset0:222 offset1:255
	s_waitcnt lgkmcnt(4)
	v_pk_mul_f32 v[72:73], v[72:73], v[48:49]
	v_pk_mul_f32 v[74:75], v[74:75], v[50:51]
	v_pk_mul_f32 v[76:77], v[76:77], v[52:53]
	v_pk_mul_f32 v[78:79], v[78:79], v[54:55]
	v_cvt_pk_bf16_f32 v96, v72, v73
	v_cvt_pk_bf16_f32 v97, v74, v75
	v_cvt_pk_bf16_f32 v98, v76, v77
	v_cvt_pk_bf16_f32 v99, v78, v79
	global_store_dwordx4 v15, v[96:99], s[42:43]
	s_add_u32 s42, s42, s44
	s_addc_u32 s43, s43, 0
	s_waitcnt lgkmcnt(0)
	v_pk_mul_f32 v[80:81], v[80:81], v[48:49]
	v_pk_mul_f32 v[82:83], v[82:83], v[50:51]
	v_pk_mul_f32 v[84:85], v[84:85], v[52:53]
	v_pk_mul_f32 v[86:87], v[86:87], v[54:55]
	v_cvt_pk_bf16_f32 v100, v80, v81
	v_cvt_pk_bf16_f32 v101, v82, v83
	v_cvt_pk_bf16_f32 v102, v84, v85
	v_cvt_pk_bf16_f32 v103, v86, v87
	global_store_dwordx4 v15, v[100:103], s[42:43]
	s_add_u32 s32, s32, 1888
	s_cmp_lt_u32 s32, 1792
	s_cbranch_scc1 .Lxp_item
	v_readlane_b32 s96, v249, 39
	v_readlane_b32 s97, v249, 40

.LBB0_517:
	s_or_b64 exec, exec, s[26:27]
	s_waitcnt lgkmcnt(0)
	ds_read_b32 v12, v60 offset:62464
	ds_read_b32 v13, v61
	ds_read_b32 v14, v62 offset:62464
	ds_read_b32 v15, v63
	ds_read_b32 v16, v64 offset:62464
	ds_read_b32 v17, v65
	ds_read_b32 v18, v66 offset:62464
	ds_read_b32 v19, v67
	ds_read_b32 v20, v68 offset:62464
	ds_read_b32 v22, v69
	ds_read_b32 v106, v70 offset:62464
	ds_read_b32 v24, v71
	ds_read_b32 v107, v72 offset:62464
	ds_read_b32 v26, v73
	s_waitcnt lgkmcnt(12)
	v_fmac_f32_e32 v13, 0, v12
	ds_read_b32 v108, v74 offset:62464
	ds_read_b32 v97, v75
	s_waitcnt lgkmcnt(12)
	v_fmac_f32_e32 v15, v13, v14
	v_mul_f32_e32 v14, v12, v14
	s_waitcnt lgkmcnt(10)
	v_fmac_f32_e32 v17, v15, v16
	v_mul_f32_e32 v16, v14, v16
	s_waitcnt lgkmcnt(8)
	v_fmac_f32_e32 v19, v17, v18
	v_mul_f32_e32 v18, v16, v18
	s_waitcnt lgkmcnt(6)
	v_fmac_f32_e32 v22, v19, v20
	v_mul_f32_e32 v23, v18, v20
	s_waitcnt lgkmcnt(4)
	v_mul_f32_e32 v25, v23, v106
	v_fmac_f32_e32 v24, v22, v106
	s_waitcnt lgkmcnt(2)
	v_mul_f32_e32 v27, v25, v107
	v_fmac_f32_e32 v26, v24, v107
	s_waitcnt lgkmcnt(0)
	v_mul_f32_e32 v98, v27, v108
	v_fmac_f32_e32 v97, v26, v108
	ds_write_b32 v50, v98
	ds_write_b32 v51, v97
	s_waitcnt lgkmcnt(0)
	s_barrier
	ds_read_b32 v109, v76
	ds_read_b32 v110, v77
	ds_read_b32 v111, v78
	ds_read_b32 v112, v79
	ds_read_b32 v113, v80
	ds_read_b32 v114, v81
	ds_read_b32 v115, v82
	ds_read_b32 v116, v83
	ds_read_b32 v117, v84
	ds_read_b32 v118, v85
	ds_read_b32 v119, v86
	ds_read_b32 v120, v87
	ds_read_b32 v121, v88
	ds_read_b32 v122, v89
	v_cndmask_b32_e64 v20, 0, v40, s[6:7]
	s_waitcnt lgkmcnt(12)
	v_fmac_f32_e32 v110, v40, v109
	ds_read_b32 v21, v90
	ds_read_b32 v40, v91
	v_cndmask_b32_e64 v20, v20, v110, s[8:9]
	s_waitcnt lgkmcnt(12)
	v_fmac_f32_e32 v112, v110, v111
	v_cndmask_b32_e64 v20, v20, v112, s[10:11]
	s_waitcnt lgkmcnt(10)
	v_fmac_f32_e32 v114, v112, v113
	v_cndmask_b32_e64 v20, v20, v114, s[12:13]
	s_waitcnt lgkmcnt(8)
	v_fmac_f32_e32 v116, v114, v115
	v_cndmask_b32_e64 v20, v20, v116, s[14:15]
	s_waitcnt lgkmcnt(6)
	v_fmac_f32_e32 v118, v116, v117
	v_cndmask_b32_e64 v20, v20, v118, s[16:17]
	s_waitcnt lgkmcnt(4)
	v_fmac_f32_e32 v120, v118, v119
	v_cndmask_b32_e64 v124, v20, v120, s[18:19]
	s_waitcnt lgkmcnt(2)
	v_fmac_f32_e32 v122, v120, v121
	v_mov_b32_e32 v20, v122
	v_cndmask_b32_e64 v99, v124, v122, s[20:21]
	v_fmac_f32_e32 v13, v12, v99
	v_fmac_f32_e32 v15, v14, v99
	v_fmac_f32_e32 v17, v16, v99
	v_add_u32_e32 v12, 0x8a00, v95
	ds_write2_b32 v12, v15, v17 offset0:64 offset1:132
	v_fmac_f32_e32 v19, v18, v99
	v_fmac_f32_e32 v22, v23, v99
	v_add_u32_e32 v12, 0x8c00, v95
	ds_write2_b32 v12, v19, v22 offset0:72 offset1:140
	v_fmac_f32_e32 v24, v25, v99
	v_fmac_f32_e32 v26, v27, v99
	v_add_u32_e32 v12, 0x8e00, v95
	v_fmac_f32_e32 v97, v98, v99
	ds_write_b32 v94, v13 offset:35584
	ds_write2_b32 v12, v24, v26 offset0:80 offset1:148
	ds_write_b32 v95, v97 offset:37216
	s_waitcnt lgkmcnt(0)
	s_barrier
	ds_read_b128 v[22:25], v96 offset:35584
	ds_read_b128 v[12:15], v96 offset:35600
	ds_read_b128 v[16:19], v44
	s_waitcnt lgkmcnt(0)
	v_lshlrev_b32_e32 v26, 16, v16
	v_mul_f32_e32 v27, 0x3d372713, v26
	v_mul_f32_e32 v27, v27, v26
	v_fma_f32 v27, v27, v26, v26
	v_mul_f32_e32 v27, 0x3f4c422a, v27
	v_mul_f32_e32 v27, 0x4038aa3b, v27
	v_exp_f32_e32 v27, v27
	v_mul_f32_e32 v26, 0.5, v26
	v_and_b32_e32 v16, 0xffff0000, v16
	v_add_f32_e32 v27, 1.0, v27
	v_rcp_f32_e32 v27, v27
	s_nop 0
	v_fma_f32 v27, v27, -2.0, 1.0
	v_add_f32_e32 v27, 1.0, v27
	v_mul_f32_e32 v26, v26, v27
	v_mul_f32_e32 v22, v22, v26
	v_mul_f32_e32 v26, 0x3d372713, v16
	v_mul_f32_e32 v26, v26, v16
	v_fma_f32 v26, v26, v16, v16
	v_mul_f32_e32 v26, 0x3f4c422a, v26
	v_mul_f32_e32 v26, 0x4038aa3b, v26
	v_exp_f32_e32 v26, v26
	v_mul_f32_e32 v16, 0.5, v16
	v_add_f32_e32 v26, 1.0, v26
	v_rcp_f32_e32 v26, v26
	s_nop 0
	v_fma_f32 v26, v26, -2.0, 1.0
	v_add_f32_e32 v26, 1.0, v26
	v_mul_f32_e32 v16, v16, v26
	v_mul_f32_e32 v16, v23, v16
	v_lshlrev_b32_e32 v23, 16, v17
	v_mul_f32_e32 v26, 0x3d372713, v23
	v_mul_f32_e32 v26, v26, v23
	v_fma_f32 v26, v26, v23, v23
	v_mul_f32_e32 v26, 0x3f4c422a, v26
	v_mul_f32_e32 v26, 0x4038aa3b, v26
	v_exp_f32_e32 v26, v26
	v_mul_f32_e32 v23, 0.5, v23
	v_and_b32_e32 v17, 0xffff0000, v17
	v_add_f32_e32 v26, 1.0, v26
	v_rcp_f32_e32 v26, v26
	s_nop 0
	v_fma_f32 v26, v26, -2.0, 1.0
	v_add_f32_e32 v26, 1.0, v26
	v_mul_f32_e32 v23, v23, v26
	v_mul_f32_e32 v23, v24, v23
	v_mul_f32_e32 v24, 0x3d372713, v17
	v_mul_f32_e32 v24, v24, v17
	v_fma_f32 v24, v24, v17, v17
	v_mul_f32_e32 v24, 0x3f4c422a, v24
	v_mul_f32_e32 v24, 0x4038aa3b, v24
	v_exp_f32_e32 v24, v24
	v_mul_f32_e32 v17, 0.5, v17
	v_add_f32_e32 v24, 1.0, v24
	v_rcp_f32_e32 v24, v24
	s_nop 0
	v_fma_f32 v24, v24, -2.0, 1.0
	v_add_f32_e32 v24, 1.0, v24
	v_mul_f32_e32 v17, v17, v24
	v_lshlrev_b32_e32 v24, 16, v18
	v_mul_f32_e32 v17, v25, v17
	v_mul_f32_e32 v25, 0x3d372713, v24
	v_mul_f32_e32 v25, v25, v24
	v_fma_f32 v25, v25, v24, v24
	v_mul_f32_e32 v25, 0x3f4c422a, v25
	v_mul_f32_e32 v25, 0x4038aa3b, v25
	v_exp_f32_e32 v25, v25
	v_mul_f32_e32 v24, 0.5, v24
	v_and_b32_e32 v18, 0xffff0000, v18
	v_add_f32_e32 v25, 1.0, v25
	v_rcp_f32_e32 v25, v25
	s_nop 0
	v_fma_f32 v25, v25, -2.0, 1.0
	v_add_f32_e32 v25, 1.0, v25
	v_mul_f32_e32 v24, v24, v25
	v_mul_f32_e32 v12, v12, v24
	v_mul_f32_e32 v24, 0x3d372713, v18
	v_mul_f32_e32 v24, v24, v18
	v_fma_f32 v24, v24, v18, v18
	v_mul_f32_e32 v24, 0x3f4c422a, v24
	v_mul_f32_e32 v24, 0x4038aa3b, v24
	v_exp_f32_e32 v24, v24
	v_mul_f32_e32 v18, 0.5, v18
	v_add_f32_e32 v24, 1.0, v24
	v_rcp_f32_e32 v24, v24
	s_nop 0
	v_fma_f32 v24, v24, -2.0, 1.0
	v_add_f32_e32 v24, 1.0, v24
	v_mul_f32_e32 v18, v18, v24
	v_mul_f32_e32 v13, v13, v18
	v_lshlrev_b32_e32 v18, 16, v19
	v_mul_f32_e32 v24, 0x3d372713, v18
	v_mul_f32_e32 v24, v24, v18
	v_fma_f32 v24, v24, v18, v18
	v_mul_f32_e32 v24, 0x3f4c422a, v24
	v_mul_f32_e32 v24, 0x4038aa3b, v24
	v_exp_f32_e32 v24, v24
	v_mul_f32_e32 v18, 0.5, v18
	v_add_f32_e32 v24, 1.0, v24
	v_rcp_f32_e32 v24, v24
	s_nop 0
	v_fma_f32 v24, v24, -2.0, 1.0
	v_add_f32_e32 v24, 1.0, v24
	v_mul_f32_e32 v18, v18, v24
	v_mul_f32_e32 v14, v14, v18
	v_and_b32_e32 v18, 0xffff0000, v19
	v_mul_f32_e32 v19, 0x3d372713, v18
	v_mul_f32_e32 v19, v19, v18
	v_fma_f32 v19, v19, v18, v18
	v_mul_f32_e32 v19, 0x3f4c422a, v19
	v_mul_f32_e32 v19, 0x4038aa3b, v19
	v_exp_f32_e32 v19, v19
	v_mul_f32_e32 v18, 0.5, v18
	v_and_b32_e32 v24, 64, v190
	v_add_u32_e32 v24, 64, v24
	v_add_f32_e32 v19, 1.0, v19
	v_rcp_f32_e32 v19, v19
	s_nop 0
	v_fma_f32 v19, v19, -2.0, 1.0
	v_add_f32_e32 v19, 1.0, v19
	v_mul_f32_e32 v18, v18, v19
	v_mul_f32_e32 v15, v15, v18
	v_mul_f32_e32 v18, v16, v16
	v_mul_f32_e32 v19, v17, v17
	v_fmac_f32_e32 v18, v22, v22
	v_fmac_f32_e32 v19, v23, v23
	v_add_f32_e32 v18, v18, v19
	v_mul_f32_e32 v19, v13, v13
	v_fmac_f32_e32 v19, v12, v12
	v_add_f32_e32 v18, v19, v18
	v_mul_f32_e32 v19, v15, v15
	v_fmac_f32_e32 v19, v14, v14
	v_add_f32_e32 v18, v19, v18
	v_xor_b32_e32 v19, 1, v190
	v_cmp_lt_i32_e32 vcc, v19, v24
	s_nop 1
	v_cndmask_b32_e32 v19, v190, v19, vcc
	v_lshlrev_b32_e32 v19, 2, v19
	ds_bpermute_b32 v19, v19, v18
	s_waitcnt lgkmcnt(0)
	v_add_f32_e32 v18, v18, v19
	v_xor_b32_e32 v19, 2, v190
	v_cmp_lt_i32_e32 vcc, v19, v24
	s_nop 1
	v_cndmask_b32_e32 v19, v190, v19, vcc
	v_lshlrev_b32_e32 v19, 2, v19
	ds_bpermute_b32 v19, v19, v18
	s_waitcnt lgkmcnt(0)
	v_add_f32_e32 v18, v18, v19
	v_xor_b32_e32 v19, 4, v190
	v_cmp_lt_i32_e32 vcc, v19, v24
	s_nop 1
	v_cndmask_b32_e32 v19, v190, v19, vcc
	v_lshlrev_b32_e32 v19, 2, v19
	ds_bpermute_b32 v19, v19, v18
	s_and_saveexec_b64 vcc, s[22:23]
	s_cbranch_execz .LBB0_510
	v_cvt_pk_bf16_f32 v22, v22, v16
	v_cvt_pk_bf16_f32 v23, v23, v17
	v_cvt_pk_bf16_f32 v24, v12, v13
	v_lshl_add_u64 v[12:13], s[30:31], 0, v[36:37]
	v_cvt_pk_bf16_f32 v25, v14, v15
	global_store_dwordx4 v[12:13], v[22:25], off
	s_and_b64 exec, exec, s[4:5]
	s_cbranch_execz .LBB0_510
	s_waitcnt lgkmcnt(0)
	v_add_f32_e32 v14, v18, v19
	v_lshl_add_u64 v[12:13], s[30:31], 0, v[34:35]
	global_store_dword v[12:13], v14, off
	s_branch .LBB0_510

.LBB0_800:
	s_andn2_b64 vcc, exec, s[0:1]
	s_cbranch_vccnz .LBB0_912
	v_readlane_b32 s0, v249, 0
	s_add_i32 s0, s0, -8
	s_cmpk_gt_u32 s0, 0xf7
	s_cbranch_scc1 .LBB0_912
	v_readlane_b32 s0, v249, 0
	s_lshl_b32 s0, s0, 3
	s_sub_i32 s0, s0, 64
	v_add_u32_e32 v0, s0, v61
	v_add_u32_e32 v61, 0x700, v0
	s_movk_i32 s0, 0x1780
	v_cmp_gt_u32_e32 vcc, s0, v61
	s_and_saveexec_b64 s[10:11], vcc
	s_cbranch_execz .LBB0_911
	v_readfirstlane_b32 s32, v61
	v_and_b32_e32 v4, 63, v188
	v_and_b32_e32 v5, 31, v188
	v_lshlrev_b32_e32 v5, 2, v5
	v_lshrrev_b32_e32 v6, 5, v4
	v_and_b32_e32 v7, 7, v188
	v_lshrrev_b32_e32 v8, 3, v4
	v_lshrrev_b32_e32 v9, 6, v188
	v_lshlrev_b32_e32 v9, 14, v9
	v_mul_u32_u24_e32 v10, 0x84, v6
	v_add3_u32 v10, v10, v5, v9
	v_mul_u32_u24_e32 v11, 0x420, v7
	v_lshl_add_u32 v11, v8, 2, v11
	v_add_u32_e32 v11, v11, v9
	v_lshlrev_b32_e32 v12, 5, v7
	v_lshlrev_b32_e32 v13, 4, v7
.Lxq_item:
	s_sub_u32 s33, s32, 1792
	s_cmp_lt_u32 s33, 1408
	s_cbranch_scc1 .Lxq_t2
	s_sub_u32 s33, s32, 3200
	s_cmp_lt_u32 s33, 1408
	s_cbranch_scc1 .Lxq_t3
	s_sub_u32 s33, s32, 4608
	s_lshr_b32 s34, s33, 5
	s_and_b32 s35, s33, 31
	s_lshl_b32 s34, s34, 6
	s_lshl_b32 s35, s35, 5
	v_readlane_b32 s50, v249, 35
	v_readlane_b32 s51, v249, 36
	s_movk_i32 s45, 0x1000
	s_movk_i32 s48, 0x1600
	s_add_u32 s60, s30, 0x1600000
	s_addc_u32 s61, s31, 0
	s_mov_b32 s52, s35
	s_mov_b32 s49, 0
	s_branch .Lxq_common
.Lxq_t2:
	s_sub_u32 s33, s32, 1792
	s_mul_hi_u32 s34, s33, 48806447
	s_mul_i32 s39, s34, 88
	s_sub_u32 s35, s33, s39
	s_lshl_b32 s34, s34, 6
	s_lshl_b32 s35, s35, 5
	v_readlane_b32 s50, v249, 31
	v_readlane_b32 s51, v249, 32
	s_movk_i32 s45, 0x2c00
	s_movk_i32 s48, 0x800
	s_add_u32 s60, s30, 0xb00000
	s_addc_u32 s61, s31, 0
	s_lshr_b32 s52, s35, 7
	s_lshl_b32 s52, s52, 8
	s_and_b32 s39, s35, 127
	s_add_u32 s52, s52, s39
	s_mov_b32 s49, 1
	v_readlane_b32 s54, v249, 29
	v_readlane_b32 s55, v249, 30
	s_lshl_b32 s39, s34, 2
	s_add_u32 s40, s54, s39
	s_addc_u32 s41, s55, 0
	s_branch .Lxq_common
.Lxq_t3:
	s_sub_u32 s33, s32, 3200
	s_mul_hi_u32 s34, s33, 48806447
	s_mul_i32 s39, s34, 88
	s_sub_u32 s35, s33, s39
	s_lshl_b32 s34, s34, 6
	s_lshl_b32 s35, s35, 5
	v_readlane_b32 s50, v249, 33
	v_readlane_b32 s51, v249, 34
	s_movk_i32 s45, 0x2c00
	s_movk_i32 s48, 0x800
	s_add_u32 s60, s30, 0xb00000
	s_addc_u32 s61, s31, 0
	s_lshr_b32 s52, s35, 7
	s_lshl_b32 s52, s52, 8
	s_and_b32 s39, s35, 127
	s_add_u32 s52, s52, s39
	s_add_u32 s52, s52, 128
	s_mov_b32 s49, 1
	v_readlane_b32 s54, v249, 29
	v_readlane_b32 s55, v249, 30
	s_lshl_b32 s39, s34, 2
	s_add_u32 s40, s54, s39
	s_addc_u32 s41, s55, 0

.Lxq_ld:
	global_load_dword v16, v14, s[36:37]
	s_add_u32 s36, s36, s38
	s_addc_u32 s37, s37, 0
	global_load_dword v17, v14, s[36:37]
	s_add_u32 s36, s36, s38
	s_addc_u32 s37, s37, 0
	global_load_dword v18, v14, s[36:37]
	s_add_u32 s36, s36, s38
	s_addc_u32 s37, s37, 0
	global_load_dword v19, v14, s[36:37]
	s_add_u32 s36, s36, s38
	s_addc_u32 s37, s37, 0
	global_load_dword v20, v14, s[36:37]
	s_add_u32 s36, s36, s38
	s_addc_u32 s37, s37, 0
	global_load_dword v21, v14, s[36:37]
	s_add_u32 s36, s36, s38
	s_addc_u32 s37, s37, 0
	global_load_dword v22, v14, s[36:37]
	s_add_u32 s36, s36, s38
	s_addc_u32 s37, s37, 0
	global_load_dword v23, v14, s[36:37]
	s_add_u32 s36, s36, s38
	s_addc_u32 s37, s37, 0
	global_load_dword v24, v14, s[36:37]
	s_add_u32 s36, s36, s38
	s_addc_u32 s37, s37, 0
	global_load_dword v25, v14, s[36:37]
	s_add_u32 s36, s36, s38
	s_addc_u32 s37, s37, 0
	global_load_dword v26, v14, s[36:37]
	s_add_u32 s36, s36, s38
	s_addc_u32 s37, s37, 0
	global_load_dword v27, v14, s[36:37]
	s_add_u32 s36, s36, s38
	s_addc_u32 s37, s37, 0
	global_load_dword v28, v14, s[36:37]
	s_add_u32 s36, s36, s38
	s_addc_u32 s37, s37, 0
	global_load_dword v29, v14, s[36:37]
	s_add_u32 s36, s36, s38
	s_addc_u32 s37, s37, 0
	global_load_dword v30, v14, s[36:37]
	s_add_u32 s36, s36, s38
	s_addc_u32 s37, s37, 0
	global_load_dword v31, v14, s[36:37]
	s_add_u32 s36, s36, s38
	s_addc_u32 s37, s37, 0
	global_load_dword v32, v14, s[36:37]
	s_add_u32 s36, s36, s38
	s_addc_u32 s37, s37, 0
	global_load_dword v33, v14, s[36:37]
	s_add_u32 s36, s36, s38
	s_addc_u32 s37, s37, 0
	global_load_dword v34, v14, s[36:37]
	s_add_u32 s36, s36, s38
	s_addc_u32 s37, s37, 0
	global_load_dword v35, v14, s[36:37]
	s_add_u32 s36, s36, s38
	s_addc_u32 s37, s37, 0
	global_load_dword v36, v14, s[36:37]
	s_add_u32 s36, s36, s38
	s_addc_u32 s37, s37, 0
	global_load_dword v37, v14, s[36:37]
	s_add_u32 s36, s36, s38
	s_addc_u32 s37, s37, 0
	global_load_dword v38, v14, s[36:37]
	s_add_u32 s36, s36, s38
	s_addc_u32 s37, s37, 0
	global_load_dword v39, v14, s[36:37]
	s_add_u32 s36, s36, s38
	s_addc_u32 s37, s37, 0
	global_load_dword v40, v14, s[36:37]
	s_add_u32 s36, s36, s38
	s_addc_u32 s37, s37, 0
	global_load_dword v41, v14, s[36:37]
	s_add_u32 s36, s36, s38
	s_addc_u32 s37, s37, 0
	global_load_dword v42, v14, s[36:37]
	s_add_u32 s36, s36, s38
	s_addc_u32 s37, s37, 0
	global_load_dword v43, v14, s[36:37]
	s_add_u32 s36, s36, s38
	s_addc_u32 s37, s37, 0
	global_load_dword v44, v14, s[36:37]
	s_add_u32 s36, s36, s38
	s_addc_u32 s37, s37, 0
	global_load_dword v45, v14, s[36:37]
	s_add_u32 s36, s36, s38
	s_addc_u32 s37, s37, 0
	global_load_dword v46, v14, s[36:37]
	s_add_u32 s36, s36, s38
	s_addc_u32 s37, s37, 0
	global_load_dword v47, v14, s[36:37]
	s_waitcnt vmcnt(31)
	ds_write_b32 v10, v16
	s_waitcnt vmcnt(30)
	ds_write_b32 v10, v17 offset:264
	s_waitcnt vmcnt(29)
	ds_write_b32 v10, v18 offset:528
	s_waitcnt vmcnt(28)
	ds_write_b32 v10, v19 offset:792
	s_waitcnt vmcnt(27)
	ds_write_b32 v10, v20 offset:1056
	s_waitcnt vmcnt(26)
	ds_write_b32 v10, v21 offset:1320
	s_waitcnt vmcnt(25)
	ds_write_b32 v10, v22 offset:1584
	s_waitcnt vmcnt(24)
	ds_write_b32 v10, v23 offset:1848
	s_waitcnt vmcnt(23)
	ds_write_b32 v10, v24 offset:2112
	s_waitcnt vmcnt(22)
	ds_write_b32 v10, v25 offset:2376
	s_waitcnt vmcnt(21)
	ds_write_b32 v10, v26 offset:2640
	s_waitcnt vmcnt(20)
	ds_write_b32 v10, v27 offset:2904
	s_waitcnt vmcnt(19)
	ds_write_b32 v10, v28 offset:3168
	s_waitcnt vmcnt(18)
	ds_write_b32 v10, v29 offset:3432
	s_waitcnt vmcnt(17)
	ds_write_b32 v10, v30 offset:3696
	s_waitcnt vmcnt(16)
	ds_write_b32 v10, v31 offset:3960
	s_waitcnt vmcnt(15)
	ds_write_b32 v10, v32 offset:4224
	s_waitcnt vmcnt(14)
	ds_write_b32 v10, v33 offset:4488
	s_waitcnt vmcnt(13)
	ds_write_b32 v10, v34 offset:4752
	s_waitcnt vmcnt(12)
	ds_write_b32 v10, v35 offset:5016
	s_waitcnt vmcnt(11)
	ds_write_b32 v10, v36 offset:5280
	s_waitcnt vmcnt(10)
	ds_write_b32 v10, v37 offset:5544
	s_waitcnt vmcnt(9)
	ds_write_b32 v10, v38 offset:5808
	s_waitcnt vmcnt(8)
	ds_write_b32 v10, v39 offset:6072
	s_waitcnt vmcnt(7)
	ds_write_b32 v10, v40 offset:6336
	s_waitcnt vmcnt(6)
	ds_write_b32 v10, v41 offset:6600
	s_waitcnt vmcnt(5)
	ds_write_b32 v10, v42 offset:6864
	s_waitcnt vmcnt(4)
	ds_write_b32 v10, v43 offset:7128
	s_waitcnt vmcnt(3)
	ds_write_b32 v10, v44 offset:7392
	s_waitcnt vmcnt(2)
	ds_write_b32 v10, v45 offset:7656
	s_waitcnt vmcnt(1)
	ds_write_b32 v10, v46 offset:7920
	s_waitcnt vmcnt(0)
	ds_write_b32 v10, v47 offset:8184
	s_waitcnt lgkmcnt(0)
	ds_read2_b32 v[56:57], v11 offset0:0 offset1:33
	ds_read2_b32 v[58:59], v11 offset0:66 offset1:99
	ds_read2_b32 v[60:61], v11 offset0:132 offset1:165
	ds_read2_b32 v[62:63], v11 offset0:198 offset1:231
	ds_read2_b32 v[64:65], v11 offset0:8 offset1:41
	ds_read2_b32 v[66:67], v11 offset0:74 offset1:107
	ds_read2_b32 v[68:69], v11 offset0:140 offset1:173
	ds_read2_b32 v[70:71], v11 offset0:206 offset1:239
	s_waitcnt lgkmcnt(4)
	v_pk_mul_f32 v[56:57], v[56:57], v[48:49]
	v_pk_mul_f32 v[58:59], v[58:59], v[50:51]
	v_pk_mul_f32 v[60:61], v[60:61], v[52:53]
	v_pk_mul_f32 v[62:63], v[62:63], v[54:55]
	v_cvt_pk_bf16_f32 v88, v56, v57
	v_cvt_pk_bf16_f32 v89, v58, v59
	v_cvt_pk_bf16_f32 v90, v60, v61
	v_cvt_pk_bf16_f32 v91, v62, v63
	global_store_dwordx4 v15, v[88:91], s[42:43]
	s_add_u32 s42, s42, s44
	s_addc_u32 s43, s43, 0
	ds_read2_b32 v[72:73], v11 offset0:16 offset1:49
	ds_read2_b32 v[74:75], v11 offset0:82 offset1:115
	ds_read2_b32 v[76:77], v11 offset0:148 offset1:181
	ds_read2_b32 v[78:79], v11 offset0:214 offset1:247
	s_waitcnt lgkmcnt(4)
	v_pk_mul_f32 v[64:65], v[64:65], v[48:49]
	v_pk_mul_f32 v[66:67], v[66:67], v[50:51]
	v_pk_mul_f32 v[68:69], v[68:69], v[52:53]
	v_pk_mul_f32 v[70:71], v[70:71], v[54:55]
	v_cvt_pk_bf16_f32 v92, v64, v65
	v_cvt_pk_bf16_f32 v93, v66, v67
	v_cvt_pk_bf16_f32 v94, v68, v69
	v_cvt_pk_bf16_f32 v95, v70, v71
	global_store_dwordx4 v15, v[92:95], s[42:43]
	s_add_u32 s42, s42, s44
	s_addc_u32 s43, s43, 0
	ds_read2_b32 v[80:81], v11 offset0:24 offset1:57
	ds_read2_b32 v[82:83], v11 offset0:90 offset1:123
	ds_read2_b32 v[84:85], v11 offset0:156 offset1:189
	ds_read2_b32 v[86:87], v11 offset0:222 offset1:255
	s_waitcnt lgkmcnt(4)
	v_pk_mul_f32 v[72:73], v[72:73], v[48:49]
	v_pk_mul_f32 v[74:75], v[74:75], v[50:51]
	v_pk_mul_f32 v[76:77], v[76:77], v[52:53]
	v_pk_mul_f32 v[78:79], v[78:79], v[54:55]
	v_cvt_pk_bf16_f32 v96, v72, v73
	v_cvt_pk_bf16_f32 v97, v74, v75
	v_cvt_pk_bf16_f32 v98, v76, v77
	v_cvt_pk_bf16_f32 v99, v78, v79
	global_store_dwordx4 v15, v[96:99], s[42:43]
	s_add_u32 s42, s42, s44
	s_addc_u32 s43, s43, 0
	s_waitcnt lgkmcnt(0)
	v_pk_mul_f32 v[80:81], v[80:81], v[48:49]
	v_pk_mul_f32 v[82:83], v[82:83], v[50:51]
	v_pk_mul_f32 v[84:85], v[84:85], v[52:53]
	v_pk_mul_f32 v[86:87], v[86:87], v[54:55]
	v_cvt_pk_bf16_f32 v100, v80, v81
	v_cvt_pk_bf16_f32 v101, v82, v83
	v_cvt_pk_bf16_f32 v102, v84, v85
	v_cvt_pk_bf16_f32 v103, v86, v87
	global_store_dwordx4 v15, v[100:103], s[42:43]
	s_add_u32 s32, s32, 1984
	s_cmp_lt_u32 s32, 6016
	s_cbranch_scc1 .Lxq_item
